# out-proj: next tile's row-scale partial sums loaded at the start of the seg-2 K-loop by all 512 threads (16 regs each) and reduced in the epilogue with a DPP pair exchange: removes one serialized load
# speedup vs baseline: 1.0008x; 1.0008x over previous
.LBB0_643:
	s_cmp_lg_u32 s89, 2
	s_cbranch_scc1 .Lsc_skip
	s_and_b64 vcc, exec, s[4:5]
	s_cbranch_vccz .Lsc_skip
	v_lshrrev_b32_e32 v232, 1, v197
	v_lshl_add_u32 v232, s87, 8, v232
	v_and_b32_e32 v234, 1, v197
	v_ashrrev_i32_e32 v233, 31, v232
	v_lshlrev_b64 v[232:233], 7, v[232:233]
	v_lshl_add_u64 v[232:233], s[20:21], 0, v[232:233]
	v_lshlrev_b32_e32 v234, 6, v234
	v_mov_b32_e32 v235, 0
	v_lshl_add_u64 v[248:249], v[232:233], 0, v[234:235]
	global_load_dwordx4 v[232:235], v[248:249], off
	global_load_dwordx4 v[236:239], v[248:249], off offset:16
	global_load_dwordx4 v[240:243], v[248:249], off offset:32
	global_load_dwordx4 v[244:247], v[248:249], off offset:48

.LBB0_648:
	s_and_saveexec_b64 s[68:69], s[4:5]
	s_cbranch_execz .LBB0_650
	v_pk_add_f32 v[232:233], v[232:233], v[236:237]
	v_pk_add_f32 v[234:235], v[234:235], v[238:239]
	v_pk_add_f32 v[240:241], v[240:241], v[244:245]
	v_pk_add_f32 v[242:243], v[242:243], v[246:247]
	v_pk_add_f32 v[232:233], v[232:233], v[240:241]
	v_pk_add_f32 v[234:235], v[234:235], v[242:243]
	v_and_b32_e32 v236, 1, v197
	v_add_f32_e32 v232, v232, v233
	v_add_f32_e32 v234, v234, v235
	v_cmp_eq_u32_e32 vcc, 0, v236
	v_add_f32_e32 v232, v232, v234
	s_nop 1
	v_mov_b32_dpp v233, v232 quad_perm:[1,0,3,2] row_mask:0xf bank_mask:0xf
	s_nop 0
	v_cndmask_b32_e32 v2, v233, v232, vcc
	v_cndmask_b32_e32 v3, v232, v233, vcc
	v_mov_b32_e32 v132, 0x358637bd
	v_pk_fma_f32 v[2:3], v[2:3], s[44:45], v[132:133] op_sel_hi:[1,0,0]
	s_nop 0
	v_mul_f32_e32 v1, 0x4b800000, v2
	v_mul_f32_e32 v132, 0x4b800000, v3
	v_cmp_gt_f32_e32 vcc, s98, v2
	v_cmp_gt_f32_e64 s[6:7], s98, v3
	s_nop 0
	v_cndmask_b32_e32 v1, v2, v1, vcc
	v_cndmask_b32_e64 v3, v3, v132, s[6:7]
	v_rsq_f32_e32 v2, v1
	v_rsq_f32_e32 v3, v3
	s_nop 0
	v_pk_mul_f32 v[132:133], v[2:3], s[24:25] op_sel_hi:[1,0]
	s_nop 0
	v_cndmask_b32_e32 v1, v2, v132, vcc
	v_cndmask_b32_e64 v3, v3, v133, s[6:7]
	v_div_scale_f32 v2, s[6:7], v3, v3, v1
	v_rcp_f32_e32 v132, v2
	v_div_scale_f32 v133, vcc, v1, v3, v1
	v_fma_f32 v134, -v2, v132, 1.0
	v_fmac_f32_e32 v132, v134, v132
	v_mul_f32_e32 v134, v133, v132
	v_fma_f32 v135, -v2, v134, v133
	v_fmac_f32_e32 v134, v135, v132
	v_fma_f32 v2, -v2, v134, v133
	v_div_fmas_f32 v2, v2, v132, v134
	v_div_fixup_f32 v2, v2, v3, v1
	v_and_b32_e32 v132, -2, v197
	v_lshlrev_b32_e32 v132, 2, v132
	v_add_u32_e32 v132, 0x20000, v132
	ds_write_b64 v132, v[2:3]
